# EpiKV: V transposed stores widened (4x4 quad transpose, 64 two-byte stores -> 16 eight-byte stores per tile and wave)
# baseline (speedup 1.0000x reference)
.LBB0_542:
	s_lshr_b32 s0, s13, 1
	s_and_b32 s0, s0, 0x60
	v_lshrrev_b32_e32 v136, 2, v140
	v_and_or_b32 v136, v136, 12, s0
	s_ashr_i32 s0, s13, 2
	v_and_or_b32 v139, v140, 15, s11
	v_and_b32_e32 v141, 3, v140
	v_lshlrev_b32_e32 v142, 1, v140
	v_lshrrev_b32_e32 v140, 1, v140
	s_andn2_b32 s0, s0, 63
	v_and_b32_e32 v142, 8, v142
	v_and_b32_e32 v140, 4, v140
	v_or3_b32 v140, v140, v141, v142
	v_add_u32_e32 v141, s0, v139
	v_lshl_add_u32 v141, v141, 3, s81
	s_movk_i32 s13, 0xc0
	v_add_u32_e32 v140, s30, v140
	v_mad_u64_u32 v[142:143], s[6:7], v141, s13, v[136:137]
	v_add_u32_e32 v141, s0, v140
	v_mov_b32_e32 v143, v165
	v_cvt_pk_bf16_f32 v124, v124, v125
	v_cvt_pk_bf16_f32 v125, v126, v127
	v_lshl_add_u64 v[126:127], v[142:143], 1, s[4:5]
	v_mad_u32_u24 v164, s1, v136, v141
	global_store_dwordx2 v[126:127], v[124:125], off
	v_cvt_pk_bf16_f32 v124, v116, v117
	v_and_b32_e32 v241, 3, v188
	v_and_b32_e32 v240, 1, v188
	v_and_b32_e32 v251, 2, v188
	v_cmp_ne_u32_e64 s[100:101], 0, v240
	v_mov_b32_e32 v240, 0x5040100
	v_mov_b32_e32 v252, 0x3020706
	s_nop 0
	v_cndmask_b32_e64 v240, v240, v252, s[100:101]
	v_cmp_ne_u32_e64 s[100:101], 0, v251
	v_mul_u32_u24_e32 v252, s1, v241
	v_sub_u32_e32 v241, v252, v241
	v_mov_b32_e32 v251, 0
	v_add_u32_e32 v250, v164, v241
	v_add_u32_e32 v164, s1, v164
	v_add_u32_e32 v164, s1, v164
	s_lshl_b32 s6, s1, 4
	v_mov_b32_e32 v254, v124
	v_add_u32_e32 v164, s1, v164
	v_cvt_pk_bf16_f32 v113, v112, v113
	v_mov_b32_e32 v112, s6
	v_cvt_pk_bf16_f32 v118, v118, v119
	v_or_b32_e32 v164, 16, v142
	v_mad_u32_u24 v112, s1, v136, v112
	v_mov_b32_dpp v242, v254 quad_perm:[1,0,3,2] row_mask:0xf bank_mask:0xf
	v_mov_b32_dpp v243, v118 quad_perm:[1,0,3,2] row_mask:0xf bank_mask:0xf
	v_perm_b32 v244, v242, v254, v240
	v_perm_b32 v245, v243, v118, v240
	s_nop 0
	v_mov_b32_dpp v246, v244 quad_perm:[2,3,0,1] row_mask:0xf bank_mask:0xf
	v_mov_b32_dpp v247, v245 quad_perm:[2,3,0,1] row_mask:0xf bank_mask:0xf
	v_cndmask_b32_e64 v248, v244, v247, s[100:101]
	v_cndmask_b32_e64 v249, v246, v245, s[100:101]
	v_lshl_add_u64 v[252:253], v[250:251], 1, s[8:9]
	global_store_dwordx2 v[252:253], v[248:249], off
	v_cvt_pk_bf16_f32 v116, v120, v121
	v_lshl_add_u64 v[118:119], v[164:165], 1, s[4:5]
	v_add_u32_e32 v164, v141, v112
	v_cvt_pk_bf16_f32 v117, v122, v123
	global_store_dwordx2 v[118:119], v[116:117], off
	v_cvt_pk_bf16_f32 v116, v114, v115
	v_add_u32_e32 v250, v164, v241
	v_add_u32_e32 v164, s1, v164
	v_add_u32_e32 v164, s1, v164
	s_or_b32 s11, s0, 16
	v_mov_b32_e32 v254, v113
	v_add_u32_e32 v164, s1, v164
	v_add_u32_e32 v113, s11, v139
	v_lshl_add_u32 v113, v113, 3, s81
	v_mov_b32_dpp v242, v254 quad_perm:[1,0,3,2] row_mask:0xf bank_mask:0xf
	v_mov_b32_dpp v243, v116 quad_perm:[1,0,3,2] row_mask:0xf bank_mask:0xf
	v_perm_b32 v244, v242, v254, v240
	v_perm_b32 v245, v243, v116, v240
	s_nop 0
	v_mov_b32_dpp v246, v244 quad_perm:[2,3,0,1] row_mask:0xf bank_mask:0xf
	v_mov_b32_dpp v247, v245 quad_perm:[2,3,0,1] row_mask:0xf bank_mask:0xf
	v_cndmask_b32_e64 v248, v244, v247, s[100:101]
	v_cndmask_b32_e64 v249, v246, v245, s[100:101]
	v_lshl_add_u64 v[252:253], v[250:251], 1, s[8:9]
	global_store_dwordx2 v[252:253], v[248:249], off
	v_mad_u64_u32 v[114:115], s[6:7], v113, s13, v[136:137]
	v_add_u32_e32 v113, s11, v140
	v_mov_b32_e32 v115, v165
	v_cvt_pk_bf16_f32 v108, v108, v109
	v_cvt_pk_bf16_f32 v109, v110, v111
	v_lshl_add_u64 v[110:111], v[114:115], 1, s[4:5]
	v_mad_u32_u24 v164, s1, v136, v113
	global_store_dwordx2 v[110:111], v[108:109], off
	v_cvt_pk_bf16_f32 v108, v100, v101
	v_add_u32_e32 v250, v164, v241
	v_add_u32_e32 v164, s1, v164
	v_add_u32_e32 v164, s1, v164
	v_mov_b32_e32 v254, v108
	v_add_u32_e32 v164, s1, v164
	v_cvt_pk_bf16_f32 v102, v102, v103
	v_or_b32_e32 v164, 16, v114
	v_mov_b32_dpp v242, v254 quad_perm:[1,0,3,2] row_mask:0xf bank_mask:0xf
	v_mov_b32_dpp v243, v102 quad_perm:[1,0,3,2] row_mask:0xf bank_mask:0xf
	v_perm_b32 v244, v242, v254, v240
	v_perm_b32 v245, v243, v102, v240
	s_nop 0
	v_mov_b32_dpp v246, v244 quad_perm:[2,3,0,1] row_mask:0xf bank_mask:0xf
	v_mov_b32_dpp v247, v245 quad_perm:[2,3,0,1] row_mask:0xf bank_mask:0xf
	v_cndmask_b32_e64 v248, v244, v247, s[100:101]
	v_cndmask_b32_e64 v249, v246, v245, s[100:101]
	v_lshl_add_u64 v[252:253], v[250:251], 1, s[8:9]
	global_store_dwordx2 v[252:253], v[248:249], off
	v_cvt_pk_bf16_f32 v100, v104, v105
	v_lshl_add_u64 v[102:103], v[164:165], 1, s[4:5]
	v_add_u32_e32 v164, v113, v112
	v_cvt_pk_bf16_f32 v101, v106, v107
	global_store_dwordx2 v[102:103], v[100:101], off
	v_cvt_pk_bf16_f32 v100, v96, v97
	v_add_u32_e32 v250, v164, v241
	v_add_u32_e32 v164, s1, v164
	v_add_u32_e32 v164, s1, v164
	v_mov_b32_e32 v254, v100
	v_add_u32_e32 v164, s1, v164
	v_cvt_pk_bf16_f32 v98, v98, v99
	s_or_b32 s11, s0, 32
	v_mov_b32_dpp v242, v254 quad_perm:[1,0,3,2] row_mask:0xf bank_mask:0xf
	v_mov_b32_dpp v243, v98 quad_perm:[1,0,3,2] row_mask:0xf bank_mask:0xf
	v_perm_b32 v244, v242, v254, v240
	v_perm_b32 v245, v243, v98, v240
	s_nop 0
	v_mov_b32_dpp v246, v244 quad_perm:[2,3,0,1] row_mask:0xf bank_mask:0xf
	v_mov_b32_dpp v247, v245 quad_perm:[2,3,0,1] row_mask:0xf bank_mask:0xf
	v_cndmask_b32_e64 v248, v244, v247, s[100:101]
	v_cndmask_b32_e64 v249, v246, v245, s[100:101]
	v_lshl_add_u64 v[252:253], v[250:251], 1, s[8:9]
	global_store_dwordx2 v[252:253], v[248:249], off
	v_add_u32_e32 v96, s11, v139
	v_lshl_add_u32 v96, v96, 3, s81
	v_mad_u64_u32 v[96:97], s[6:7], v96, s13, v[136:137]
	v_add_u32_e32 v98, s11, v140
	v_mov_b32_e32 v97, v165
	v_cvt_pk_bf16_f32 v92, v92, v93
	v_cvt_pk_bf16_f32 v93, v94, v95
	v_lshl_add_u64 v[94:95], v[96:97], 1, s[4:5]
	v_mad_u32_u24 v164, s1, v136, v98
	global_store_dwordx2 v[94:95], v[92:93], off
	v_cvt_pk_bf16_f32 v92, v84, v85
	v_add_u32_e32 v250, v164, v241
	v_add_u32_e32 v164, s1, v164
	v_add_u32_e32 v164, s1, v164
	v_mov_b32_e32 v254, v92
	v_add_u32_e32 v164, s1, v164
	v_cvt_pk_bf16_f32 v86, v86, v87
	v_or_b32_e32 v164, 16, v96
	v_mov_b32_dpp v242, v254 quad_perm:[1,0,3,2] row_mask:0xf bank_mask:0xf
	v_mov_b32_dpp v243, v86 quad_perm:[1,0,3,2] row_mask:0xf bank_mask:0xf
	v_perm_b32 v244, v242, v254, v240
	v_perm_b32 v245, v243, v86, v240
	s_nop 0
	v_mov_b32_dpp v246, v244 quad_perm:[2,3,0,1] row_mask:0xf bank_mask:0xf
	v_mov_b32_dpp v247, v245 quad_perm:[2,3,0,1] row_mask:0xf bank_mask:0xf
	v_cndmask_b32_e64 v248, v244, v247, s[100:101]
	v_cndmask_b32_e64 v249, v246, v245, s[100:101]
	v_lshl_add_u64 v[252:253], v[250:251], 1, s[8:9]
	global_store_dwordx2 v[252:253], v[248:249], off
	v_cvt_pk_bf16_f32 v84, v88, v89
	v_lshl_add_u64 v[86:87], v[164:165], 1, s[4:5]
	v_add_u32_e32 v164, v98, v112
	v_cvt_pk_bf16_f32 v85, v90, v91
	global_store_dwordx2 v[86:87], v[84:85], off
	v_cvt_pk_bf16_f32 v84, v80, v81
	v_add_u32_e32 v250, v164, v241
	v_add_u32_e32 v164, s1, v164
	v_add_u32_e32 v164, s1, v164
	v_mov_b32_e32 v254, v84
	v_add_u32_e32 v164, s1, v164
	v_cvt_pk_bf16_f32 v82, v82, v83
	s_or_b32 s11, s0, 48
	v_mov_b32_dpp v242, v254 quad_perm:[1,0,3,2] row_mask:0xf bank_mask:0xf
	v_mov_b32_dpp v243, v82 quad_perm:[1,0,3,2] row_mask:0xf bank_mask:0xf
	v_perm_b32 v244, v242, v254, v240
	v_perm_b32 v245, v243, v82, v240
	s_nop 0
	v_mov_b32_dpp v246, v244 quad_perm:[2,3,0,1] row_mask:0xf bank_mask:0xf
	v_mov_b32_dpp v247, v245 quad_perm:[2,3,0,1] row_mask:0xf bank_mask:0xf
	v_cndmask_b32_e64 v248, v244, v247, s[100:101]
	v_cndmask_b32_e64 v249, v246, v245, s[100:101]
	v_lshl_add_u64 v[252:253], v[250:251], 1, s[8:9]
	global_store_dwordx2 v[252:253], v[248:249], off
	v_add_u32_e32 v80, s11, v139
	v_lshl_add_u32 v80, v80, 3, s81
	v_mad_u64_u32 v[80:81], s[6:7], v80, s13, v[136:137]
	v_add_u32_e32 v82, s11, v140
	v_mov_b32_e32 v81, v165
	v_cvt_pk_bf16_f32 v76, v76, v77
	v_cvt_pk_bf16_f32 v77, v78, v79
	v_lshl_add_u64 v[78:79], v[80:81], 1, s[4:5]
	v_mad_u32_u24 v164, s1, v136, v82
	global_store_dwordx2 v[78:79], v[76:77], off
	v_cvt_pk_bf16_f32 v76, v68, v69
	v_add_u32_e32 v250, v164, v241
	v_add_u32_e32 v164, s1, v164
	v_add_u32_e32 v164, s1, v164
	v_mov_b32_e32 v254, v76
	v_add_u32_e32 v164, s1, v164
	v_cvt_pk_bf16_f32 v70, v70, v71
	v_or_b32_e32 v164, 16, v80
	v_mov_b32_dpp v242, v254 quad_perm:[1,0,3,2] row_mask:0xf bank_mask:0xf
	v_mov_b32_dpp v243, v70 quad_perm:[1,0,3,2] row_mask:0xf bank_mask:0xf
	v_perm_b32 v244, v242, v254, v240
	v_perm_b32 v245, v243, v70, v240
	s_nop 0
	v_mov_b32_dpp v246, v244 quad_perm:[2,3,0,1] row_mask:0xf bank_mask:0xf
	v_mov_b32_dpp v247, v245 quad_perm:[2,3,0,1] row_mask:0xf bank_mask:0xf
	v_cndmask_b32_e64 v248, v244, v247, s[100:101]
	v_cndmask_b32_e64 v249, v246, v245, s[100:101]
	v_lshl_add_u64 v[252:253], v[250:251], 1, s[8:9]
	global_store_dwordx2 v[252:253], v[248:249], off
	v_cvt_pk_bf16_f32 v68, v72, v73
	v_lshl_add_u64 v[70:71], v[164:165], 1, s[4:5]
	v_add_u32_e32 v164, v82, v112
	v_cvt_pk_bf16_f32 v69, v74, v75
	global_store_dwordx2 v[70:71], v[68:69], off
	v_cvt_pk_bf16_f32 v68, v64, v65
	v_add_u32_e32 v250, v164, v241
	v_add_u32_e32 v164, s1, v164
	v_add_u32_e32 v164, s1, v164
	v_mov_b32_e32 v254, v68
	v_add_u32_e32 v164, s1, v164
	v_cvt_pk_bf16_f32 v66, v66, v67
	s_add_i32 s11, s0, 0x80
	v_mov_b32_dpp v242, v254 quad_perm:[1,0,3,2] row_mask:0xf bank_mask:0xf
	v_mov_b32_dpp v243, v66 quad_perm:[1,0,3,2] row_mask:0xf bank_mask:0xf
	v_perm_b32 v244, v242, v254, v240
	v_perm_b32 v245, v243, v66, v240
	s_nop 0
	v_mov_b32_dpp v246, v244 quad_perm:[2,3,0,1] row_mask:0xf bank_mask:0xf
	v_mov_b32_dpp v247, v245 quad_perm:[2,3,0,1] row_mask:0xf bank_mask:0xf
	v_cndmask_b32_e64 v248, v244, v247, s[100:101]
	v_cndmask_b32_e64 v249, v246, v245, s[100:101]
	v_lshl_add_u64 v[252:253], v[250:251], 1, s[8:9]
	global_store_dwordx2 v[252:253], v[248:249], off
	v_add_u32_e32 v64, s11, v139
	v_lshl_add_u32 v64, v64, 3, s81
	v_mad_u64_u32 v[64:65], s[6:7], v64, s13, v[136:137]
	v_add_u32_e32 v66, s11, v140
	v_mov_b32_e32 v65, v165
	v_cvt_pk_bf16_f32 v60, v60, v61
	v_cvt_pk_bf16_f32 v61, v62, v63
	v_lshl_add_u64 v[62:63], v[64:65], 1, s[4:5]
	v_mad_u32_u24 v164, s1, v136, v66
	global_store_dwordx2 v[62:63], v[60:61], off
	v_cvt_pk_bf16_f32 v60, v52, v53
	v_add_u32_e32 v250, v164, v241
	v_add_u32_e32 v164, s1, v164
	v_add_u32_e32 v164, s1, v164
	v_mov_b32_e32 v254, v60
	v_add_u32_e32 v164, s1, v164
	v_cvt_pk_bf16_f32 v54, v54, v55
	v_or_b32_e32 v164, 16, v64
	v_mov_b32_dpp v242, v254 quad_perm:[1,0,3,2] row_mask:0xf bank_mask:0xf
	v_mov_b32_dpp v243, v54 quad_perm:[1,0,3,2] row_mask:0xf bank_mask:0xf
	v_perm_b32 v244, v242, v254, v240
	v_perm_b32 v245, v243, v54, v240
	s_nop 0
	v_mov_b32_dpp v246, v244 quad_perm:[2,3,0,1] row_mask:0xf bank_mask:0xf
	v_mov_b32_dpp v247, v245 quad_perm:[2,3,0,1] row_mask:0xf bank_mask:0xf
	v_cndmask_b32_e64 v248, v244, v247, s[100:101]
	v_cndmask_b32_e64 v249, v246, v245, s[100:101]
	v_lshl_add_u64 v[252:253], v[250:251], 1, s[8:9]
	global_store_dwordx2 v[252:253], v[248:249], off
	v_cvt_pk_bf16_f32 v52, v56, v57
	v_lshl_add_u64 v[54:55], v[164:165], 1, s[4:5]
	v_add_u32_e32 v164, v66, v112
	v_cvt_pk_bf16_f32 v53, v58, v59
	global_store_dwordx2 v[54:55], v[52:53], off
	v_cvt_pk_bf16_f32 v52, v48, v49
	v_add_u32_e32 v250, v164, v241
	v_add_u32_e32 v164, s1, v164
	v_add_u32_e32 v164, s1, v164
	v_mov_b32_e32 v254, v52
	v_add_u32_e32 v164, s1, v164
	v_cvt_pk_bf16_f32 v50, v50, v51
	s_add_i32 s11, s0, 0x90
	v_mov_b32_dpp v242, v254 quad_perm:[1,0,3,2] row_mask:0xf bank_mask:0xf
	v_mov_b32_dpp v243, v50 quad_perm:[1,0,3,2] row_mask:0xf bank_mask:0xf
	v_perm_b32 v244, v242, v254, v240
	v_perm_b32 v245, v243, v50, v240
	s_nop 0
	v_mov_b32_dpp v246, v244 quad_perm:[2,3,0,1] row_mask:0xf bank_mask:0xf
	v_mov_b32_dpp v247, v245 quad_perm:[2,3,0,1] row_mask:0xf bank_mask:0xf
	v_cndmask_b32_e64 v248, v244, v247, s[100:101]
	v_cndmask_b32_e64 v249, v246, v245, s[100:101]
	v_lshl_add_u64 v[252:253], v[250:251], 1, s[8:9]
	global_store_dwordx2 v[252:253], v[248:249], off
	v_add_u32_e32 v48, s11, v139
	v_lshl_add_u32 v48, v48, 3, s81
	v_mad_u64_u32 v[48:49], s[6:7], v48, s13, v[136:137]
	v_add_u32_e32 v50, s11, v140
	v_mov_b32_e32 v49, v165
	v_cvt_pk_bf16_f32 v44, v44, v45
	v_cvt_pk_bf16_f32 v45, v46, v47
	v_lshl_add_u64 v[46:47], v[48:49], 1, s[4:5]
	v_mad_u32_u24 v164, s1, v136, v50
	global_store_dwordx2 v[46:47], v[44:45], off
	v_cvt_pk_bf16_f32 v44, v36, v37
	v_add_u32_e32 v250, v164, v241
	v_add_u32_e32 v164, s1, v164
	v_add_u32_e32 v164, s1, v164
	v_mov_b32_e32 v254, v44
	v_add_u32_e32 v164, s1, v164
	v_cvt_pk_bf16_f32 v38, v38, v39
	v_or_b32_e32 v164, 16, v48
	v_mov_b32_dpp v242, v254 quad_perm:[1,0,3,2] row_mask:0xf bank_mask:0xf
	v_mov_b32_dpp v243, v38 quad_perm:[1,0,3,2] row_mask:0xf bank_mask:0xf
	v_perm_b32 v244, v242, v254, v240
	v_perm_b32 v245, v243, v38, v240
	s_nop 0
	v_mov_b32_dpp v246, v244 quad_perm:[2,3,0,1] row_mask:0xf bank_mask:0xf
	v_mov_b32_dpp v247, v245 quad_perm:[2,3,0,1] row_mask:0xf bank_mask:0xf
	v_cndmask_b32_e64 v248, v244, v247, s[100:101]
	v_cndmask_b32_e64 v249, v246, v245, s[100:101]
	v_lshl_add_u64 v[252:253], v[250:251], 1, s[8:9]
	global_store_dwordx2 v[252:253], v[248:249], off
	v_cvt_pk_bf16_f32 v36, v40, v41
	v_lshl_add_u64 v[38:39], v[164:165], 1, s[4:5]
	v_add_u32_e32 v164, v50, v112
	v_cvt_pk_bf16_f32 v37, v42, v43
	global_store_dwordx2 v[38:39], v[36:37], off
	v_cvt_pk_bf16_f32 v36, v32, v33
	v_add_u32_e32 v250, v164, v241
	v_add_u32_e32 v164, s1, v164
	v_add_u32_e32 v164, s1, v164
	v_mov_b32_e32 v254, v36
	v_add_u32_e32 v164, s1, v164
	v_cvt_pk_bf16_f32 v34, v34, v35
	s_add_i32 s11, s0, 0xa0
	v_mov_b32_dpp v242, v254 quad_perm:[1,0,3,2] row_mask:0xf bank_mask:0xf
	v_mov_b32_dpp v243, v34 quad_perm:[1,0,3,2] row_mask:0xf bank_mask:0xf
	v_perm_b32 v244, v242, v254, v240
	v_perm_b32 v245, v243, v34, v240
	s_nop 0
	v_mov_b32_dpp v246, v244 quad_perm:[2,3,0,1] row_mask:0xf bank_mask:0xf
	v_mov_b32_dpp v247, v245 quad_perm:[2,3,0,1] row_mask:0xf bank_mask:0xf
	v_cndmask_b32_e64 v248, v244, v247, s[100:101]
	v_cndmask_b32_e64 v249, v246, v245, s[100:101]
	v_lshl_add_u64 v[252:253], v[250:251], 1, s[8:9]
	global_store_dwordx2 v[252:253], v[248:249], off
	v_add_u32_e32 v32, s11, v139
	v_lshl_add_u32 v32, v32, 3, s81
	v_mad_u64_u32 v[32:33], s[6:7], v32, s13, v[136:137]
	v_add_u32_e32 v34, s11, v140
	v_mov_b32_e32 v33, v165
	v_cvt_pk_bf16_f32 v28, v28, v29
	v_cvt_pk_bf16_f32 v29, v30, v31
	v_lshl_add_u64 v[30:31], v[32:33], 1, s[4:5]
	v_mad_u32_u24 v164, s1, v136, v34
	global_store_dwordx2 v[30:31], v[28:29], off
	v_cvt_pk_bf16_f32 v28, v20, v21
	v_add_u32_e32 v250, v164, v241
	v_add_u32_e32 v164, s1, v164
	v_add_u32_e32 v164, s1, v164
	v_mov_b32_e32 v254, v28
	v_add_u32_e32 v164, s1, v164
	v_cvt_pk_bf16_f32 v22, v22, v23
	v_or_b32_e32 v164, 16, v32
	v_mov_b32_dpp v242, v254 quad_perm:[1,0,3,2] row_mask:0xf bank_mask:0xf
	v_mov_b32_dpp v243, v22 quad_perm:[1,0,3,2] row_mask:0xf bank_mask:0xf
	v_perm_b32 v244, v242, v254, v240
	v_perm_b32 v245, v243, v22, v240
	s_nop 0
	v_mov_b32_dpp v246, v244 quad_perm:[2,3,0,1] row_mask:0xf bank_mask:0xf
	v_mov_b32_dpp v247, v245 quad_perm:[2,3,0,1] row_mask:0xf bank_mask:0xf
	v_cndmask_b32_e64 v248, v244, v247, s[100:101]
	v_cndmask_b32_e64 v249, v246, v245, s[100:101]
	v_lshl_add_u64 v[252:253], v[250:251], 1, s[8:9]
	global_store_dwordx2 v[252:253], v[248:249], off
	v_cvt_pk_bf16_f32 v20, v24, v25
	v_lshl_add_u64 v[22:23], v[164:165], 1, s[4:5]
	v_add_u32_e32 v164, v34, v112
	v_cvt_pk_bf16_f32 v21, v26, v27
	global_store_dwordx2 v[22:23], v[20:21], off
	v_cvt_pk_bf16_f32 v20, v16, v17
	v_add_u32_e32 v250, v164, v241
	v_add_u32_e32 v164, s1, v164
	v_add_u32_e32 v164, s1, v164
	v_mov_b32_e32 v254, v20
	v_add_u32_e32 v164, s1, v164
	v_cvt_pk_bf16_f32 v18, v18, v19
	s_addk_i32 s0, 0xb0
	v_mov_b32_dpp v242, v254 quad_perm:[1,0,3,2] row_mask:0xf bank_mask:0xf
	v_mov_b32_dpp v243, v18 quad_perm:[1,0,3,2] row_mask:0xf bank_mask:0xf
	v_perm_b32 v244, v242, v254, v240
	v_perm_b32 v245, v243, v18, v240
	s_nop 0
	v_mov_b32_dpp v246, v244 quad_perm:[2,3,0,1] row_mask:0xf bank_mask:0xf
	v_mov_b32_dpp v247, v245 quad_perm:[2,3,0,1] row_mask:0xf bank_mask:0xf
	v_cndmask_b32_e64 v248, v244, v247, s[100:101]
	v_cndmask_b32_e64 v249, v246, v245, s[100:101]
	v_lshl_add_u64 v[252:253], v[250:251], 1, s[8:9]
	global_store_dwordx2 v[252:253], v[248:249], off
	v_add_u32_e32 v16, s0, v139
	v_lshl_add_u32 v16, v16, 3, s81
	v_mad_u64_u32 v[16:17], s[6:7], v16, s13, v[136:137]
	v_add_u32_e32 v18, s0, v140
	v_mov_b32_e32 v17, v165
	v_cvt_pk_bf16_f32 v12, v12, v13
	v_cvt_pk_bf16_f32 v13, v14, v15
	v_lshl_add_u64 v[14:15], v[16:17], 1, s[4:5]
	v_mad_u32_u24 v164, s1, v136, v18
	global_store_dwordx2 v[14:15], v[12:13], off
	v_cvt_pk_bf16_f32 v12, v4, v5
	v_add_u32_e32 v250, v164, v241
	v_add_u32_e32 v164, s1, v164
	v_add_u32_e32 v164, s1, v164
	v_mov_b32_e32 v254, v12
	v_add_u32_e32 v164, s1, v164
	v_cvt_pk_bf16_f32 v6, v6, v7
	v_or_b32_e32 v164, 16, v16
	v_mov_b32_dpp v242, v254 quad_perm:[1,0,3,2] row_mask:0xf bank_mask:0xf
	v_mov_b32_dpp v243, v6 quad_perm:[1,0,3,2] row_mask:0xf bank_mask:0xf
	v_perm_b32 v244, v242, v254, v240
	v_perm_b32 v245, v243, v6, v240
	s_nop 0
	v_mov_b32_dpp v246, v244 quad_perm:[2,3,0,1] row_mask:0xf bank_mask:0xf
	v_mov_b32_dpp v247, v245 quad_perm:[2,3,0,1] row_mask:0xf bank_mask:0xf
	v_cndmask_b32_e64 v248, v244, v247, s[100:101]
	v_cndmask_b32_e64 v249, v246, v245, s[100:101]
	v_lshl_add_u64 v[252:253], v[250:251], 1, s[8:9]
	global_store_dwordx2 v[252:253], v[248:249], off
	v_cvt_pk_bf16_f32 v4, v8, v9
	v_lshl_add_u64 v[6:7], v[164:165], 1, s[4:5]
	v_add_u32_e32 v164, v18, v112
	v_cvt_pk_bf16_f32 v5, v10, v11
	global_store_dwordx2 v[6:7], v[4:5], off
	v_cvt_pk_bf16_f32 v4, v0, v1
	v_add_u32_e32 v250, v164, v241
	v_add_u32_e32 v164, s1, v164
	v_add_u32_e32 v164, s1, v164
	v_mov_b32_e32 v254, v4
	v_add_u32_e32 v164, s1, v164
	v_cvt_pk_bf16_f32 v2, v2, v3
	s_and_b64 vcc, exec, s[16:17]
	s_mov_b32 s0, s10
	s_mov_b32 s81, s12
	s_mov_b64 s[30:31], s[20:21]
	s_mov_b64 s[36:37], s[14:15]
	v_mov_b32_dpp v242, v254 quad_perm:[1,0,3,2] row_mask:0xf bank_mask:0xf
	v_mov_b32_dpp v243, v2 quad_perm:[1,0,3,2] row_mask:0xf bank_mask:0xf
	v_perm_b32 v244, v242, v254, v240
	v_perm_b32 v245, v243, v2, v240
	s_nop 0
	v_mov_b32_dpp v246, v244 quad_perm:[2,3,0,1] row_mask:0xf bank_mask:0xf
	v_mov_b32_dpp v247, v245 quad_perm:[2,3,0,1] row_mask:0xf bank_mask:0xf
	v_cndmask_b32_e64 v248, v244, v247, s[100:101]
	v_cndmask_b32_e64 v249, v246, v245, s[100:101]
	v_lshl_add_u64 v[252:253], v[250:251], 1, s[8:9]
	global_store_dwordx2 v[252:253], v[248:249], off
	s_cbranch_vccnz .LBB0_560
